# attention row-max chains: x=max(x,x) canonicalisations dropped, chains start with v_max3 (20 fewer VALU per 2 key tiles); on top of v87
# speedup vs baseline: 1.0095x; 1.0014x over previous
.LBB0_732:
	ds_read_b128 v[110:113], v182
	ds_read_b128 v[122:125], v182 offset:64
	ds_read_b128 v[118:121], v182 offset:3328
	ds_read_b128 v[136:139], v182 offset:128
	ds_read_b128 v[140:143], v182 offset:6656
	ds_read_b128 v[148:151], v182 offset:6720
	ds_read_b128 v[152:155], v182 offset:9984
	ds_read_b128 v[156:159], v182 offset:6784
	s_waitcnt lgkmcnt(7)
	v_mfma_f32_16x16x32_bf16 v[114:117], v[110:113], v[0:3], 0
	ds_read_b128 v[164:167], v182 offset:3392
	ds_read_b128 v[186:189], v182 offset:3456
	ds_read_b128 v[190:193], v182 offset:10048
	ds_read_b128 v[194:197], v182 offset:10112
	s_add_i32 s28, s31, -3
	s_waitcnt lgkmcnt(9)
	v_mfma_f32_16x16x32_bf16 v[130:133], v[118:121], v[0:3], 0
	s_cmp_ge_u32 s28, s30
	v_mfma_f32_16x16x32_bf16 v[114:117], v[122:125], v[4:7], v[114:117]
	s_waitcnt lgkmcnt(7)
	v_mfma_f32_16x16x32_bf16 v[144:147], v[140:143], v[0:3], 0
	s_waitcnt lgkmcnt(5)
	v_mfma_f32_16x16x32_bf16 v[160:163], v[152:155], v[0:3], 0
	s_waitcnt lgkmcnt(3)
	v_mfma_f32_16x16x32_bf16 v[130:133], v[164:167], v[4:7], v[130:133]
	v_mfma_f32_16x16x32_bf16 v[114:117], v[136:139], v[16:19], v[114:117]
	v_mfma_f32_16x16x32_bf16 v[144:147], v[148:151], v[4:7], v[144:147]
	s_waitcnt lgkmcnt(1)
	v_mfma_f32_16x16x32_bf16 v[160:163], v[190:193], v[4:7], v[160:163]
	s_nop 4
	v_max3_f32 v80, v114, v115, v116
	v_mfma_f32_16x16x32_bf16 v[130:133], v[186:189], v[16:19], v[130:133]
	v_max_f32_e32 v80, v80, v117
	v_mfma_f32_16x16x32_bf16 v[198:201], v[156:159], v[16:19], v[144:147]
	s_waitcnt lgkmcnt(0)
	v_mfma_f32_16x16x32_bf16 v[160:163], v[194:197], v[16:19], v[160:163]
	s_nop 3
	v_max3_f32 v80, v80, v130, v131
	v_max3_f32 v80, v80, v132, v133
	v_max3_f32 v80, v80, v198, v199
	v_max3_f32 v80, v80, v200, v201
	v_mfma_f32_16x16x32_bf16 v[202:205], v[110:113], v[8:11], 0
	v_max3_f32 v80, v80, v160, v161
	v_max3_f32 v80, v80, v162, v163
	v_mov_b32_e32 v126, v80
	s_nop 1
	v_permlane16_swap_b32 v80, v126
	v_mfma_f32_16x16x32_bf16 v[206:209], v[118:121], v[8:11], 0
	s_waitcnt lgkmcnt(0)
	v_max_f32_e32 v80, v80, v126
	v_mov_b32_e32 v126, v80
	s_nop 1
	v_permlane32_swap_b32 v80, v126
	v_mfma_f32_16x16x32_bf16 v[140:143], v[140:143], v[8:11], 0
	s_waitcnt lgkmcnt(0)
	v_mfma_f32_16x16x32_bf16 v[152:155], v[152:155], v[8:11], 0
	v_max_f32_e32 v80, v80, v126
	v_mul_f32_e32 v80, 0x3e16c740, v80
	v_mfma_f32_16x16x32_bf16 v[202:205], v[122:125], v[12:15], v[202:205]
	v_max_f32_e32 v146, v184, v80
	v_fma_f32 v110, v114, s37, -v146
	v_exp_f32_e32 v111, v110
	v_mfma_f32_16x16x32_bf16 v[164:167], v[164:167], v[12:15], v[206:209]
	v_fma_f32 v110, v115, s37, -v146
	v_exp_f32_e32 v113, v110
	v_fma_f32 v110, v116, s37, -v146
	v_mfma_f32_16x16x32_bf16 v[140:143], v[148:151], v[12:15], v[140:143]
	v_exp_f32_e32 v115, v110
	v_fma_f32 v110, v117, s37, -v146
	v_exp_f32_e32 v117, v110
	v_mfma_f32_16x16x32_bf16 v[148:151], v[190:193], v[12:15], v[152:155]
	v_fma_f32 v110, v130, s37, -v146
	v_exp_f32_e32 v119, v110
	v_fma_f32 v110, v131, s37, -v146
	v_mfma_f32_16x16x32_bf16 v[152:155], v[136:139], v[44:47], v[202:205]
	v_exp_f32_e32 v121, v110
	v_fma_f32 v110, v132, s37, -v146
	v_exp_f32_e32 v123, v110
	v_mfma_f32_16x16x32_bf16 v[164:167], v[186:189], v[44:47], v[164:167]
	v_fma_f32 v110, v133, s37, -v146
	s_nop 2
	v_max3_f32 v112, v152, v153, v154
	v_mfma_f32_16x16x32_bf16 v[156:159], v[156:159], v[44:47], v[140:143]
	v_max_f32_e32 v112, v112, v155
	v_max3_f32 v112, v112, v164, v165
	v_max3_f32 v112, v112, v166, v167
	v_mfma_f32_16x16x32_bf16 v[148:151], v[194:197], v[44:47], v[148:151]
	v_exp_f32_e32 v127, v110
	s_nop 2
	v_max3_f32 v112, v112, v156, v157
	v_max3_f32 v112, v112, v158, v159
	v_fma_f32 v110, v198, s37, -v146
	v_exp_f32_e32 v125, v110
	v_max3_f32 v112, v112, v148, v149
	v_max3_f32 v112, v112, v150, v151
	v_mov_b32_e32 v114, v112
	s_nop 1
	v_permlane16_swap_b32 v112, v114
	v_fma_f32 v110, v199, s37, -v146
	v_exp_f32_e32 v133, v110
	v_fma_f32 v110, v200, s37, -v146
	v_exp_f32_e32 v131, v110
	s_waitcnt lgkmcnt(0)
	v_max_f32_e32 v112, v112, v114
	v_fma_f32 v110, v201, s37, -v146
	v_mov_b32_e32 v114, v112
	s_nop 1
	v_permlane32_swap_b32 v112, v114
	v_exp_f32_e32 v135, v110
	v_fma_f32 v110, v160, s37, -v146
	v_exp_f32_e32 v137, v110
	v_fma_f32 v110, v161, s37, -v146
	v_exp_f32_e32 v139, v110
	v_fma_f32 v110, v162, s37, -v146
	v_exp_f32_e32 v141, v110
	v_fma_f32 v110, v163, s37, -v146
	v_exp_f32_e32 v143, v110
	s_waitcnt lgkmcnt(0)
	v_max_f32_e32 v110, v112, v114
	v_mul_f32_e32 v110, 0x3e16c740, v110
	v_max_f32_e32 v145, v97, v110
	v_sub_f32_e32 v80, v184, v146
	v_sub_f32_e32 v97, v97, v145
	v_fma_f32 v110, v152, s37, -v145
	v_fma_f32 v112, v153, s37, -v145
	v_fma_f32 v114, v154, s37, -v145
	v_fma_f32 v116, v155, s37, -v145
	v_fma_f32 v118, v164, s37, -v145
	v_fma_f32 v120, v165, s37, -v145
	v_fma_f32 v122, v166, s37, -v145
	v_fma_f32 v124, v167, s37, -v145
	v_exp_f32_e32 v80, v80
	v_exp_f32_e32 v110, v110
	v_exp_f32_e32 v112, v112
	v_exp_f32_e32 v114, v114
	v_exp_f32_e32 v116, v116
	v_exp_f32_e32 v118, v118
	v_exp_f32_e32 v120, v120
	v_exp_f32_e32 v122, v122
	v_exp_f32_e32 v126, v124
	v_fma_f32 v136, v148, s37, -v145
	v_fma_f32 v138, v149, s37, -v145
	v_fma_f32 v140, v150, s37, -v145
	v_fma_f32 v142, v151, s37, -v145
	v_exp_f32_e32 v144, v97
	ds_read_b64_tr_b16 v[150:151], v183 offset:15872
	ds_read_b64_tr_b16 v[148:149], v183 offset:13312
	ds_read_b64_tr_b16 v[160:161], v183 offset:13344
	ds_read_b64_tr_b16 v[164:165], v183 offset:13376
	ds_read_b64_tr_b16 v[184:185], v183 offset:13408
	ds_read_b64_tr_b16 v[162:163], v183 offset:15904
	ds_read_b64_tr_b16 v[166:167], v183 offset:15936
	ds_read_b64_tr_b16 v[186:187], v183 offset:15968
	v_fma_f32 v130, v157, s37, -v145
	v_cvt_pk_bf16_f32 v152, v111, v113
	v_cvt_pk_bf16_f32 v153, v115, v117
	v_cvt_pk_bf16_f32 v154, v119, v121
	v_cvt_pk_bf16_f32 v155, v123, v127
	v_fma_f32 v124, v156, s37, -v145
	v_exp_f32_e32 v132, v130
	v_fma_f32 v130, v158, s37, -v145
	v_fma_f32 v134, v159, s37, -v145
	v_pk_mul_f32 v[78:79], v[78:79], v[80:81] op_sel_hi:[1,0]
	v_pk_mul_f32 v[76:77], v[76:77], v[80:81] op_sel_hi:[1,0]
	v_pk_mul_f32 v[74:75], v[74:75], v[80:81] op_sel_hi:[1,0]
	v_pk_mul_f32 v[70:71], v[70:71], v[144:145] op_sel_hi:[1,0]
	v_pk_mul_f32 v[68:69], v[68:69], v[144:145] op_sel_hi:[1,0]
	v_cvt_pk_bf16_f32 v156, v110, v112
	v_cvt_pk_bf16_f32 v157, v114, v116
	v_cvt_pk_bf16_f32 v158, v118, v120
	v_cvt_pk_bf16_f32 v159, v122, v126
	v_pk_mul_f32 v[72:73], v[72:73], v[80:81] op_sel_hi:[1,0]
	v_pk_mul_f32 v[66:67], v[66:67], v[80:81] op_sel_hi:[1,0]
	v_pk_mul_f32 v[64:65], v[64:65], v[80:81] op_sel_hi:[1,0]
	v_pk_mul_f32 v[62:63], v[62:63], v[80:81] op_sel_hi:[1,0]
	v_pk_mul_f32 v[58:59], v[58:59], v[144:145] op_sel_hi:[1,0]
	v_pk_mul_f32 v[56:57], v[56:57], v[144:145] op_sel_hi:[1,0]
	v_pk_mul_f32 v[60:61], v[60:61], v[80:81] op_sel_hi:[1,0]
	v_pk_mul_f32 v[54:55], v[54:55], v[144:145] op_sel_hi:[1,0]
	v_pk_mul_f32 v[52:53], v[52:53], v[144:145] op_sel_hi:[1,0]
	v_pk_mul_f32 v[50:51], v[50:51], v[144:145] op_sel_hi:[1,0]
	v_pk_mul_f32 v[48:49], v[48:49], v[144:145] op_sel_hi:[1,0]
	v_exp_f32_e32 v124, v124
	v_exp_f32_e32 v130, v130
	v_exp_f32_e32 v134, v134
	v_exp_f32_e32 v136, v136
	v_exp_f32_e32 v138, v138
	v_exp_f32_e32 v140, v140
	v_exp_f32_e32 v142, v142
	s_waitcnt lgkmcnt(6)
	v_mfma_f32_16x16x32_bf16 v[76:79], v[148:151], v[152:155], v[76:79]
	v_mfma_f32_16x16x32_bf16 v[68:71], v[148:151], v[156:159], v[68:71]
	s_waitcnt lgkmcnt(2)
	v_mfma_f32_16x16x32_bf16 v[148:151], v[160:163], v[152:155], v[72:75]
	v_mfma_f32_16x16x32_bf16 v[56:59], v[160:163], v[156:159], v[56:59]
	v_cvt_pk_bf16_f32 v160, v125, v133
	v_cvt_pk_bf16_f32 v161, v131, v135
	v_cvt_pk_bf16_f32 v162, v137, v139
	s_waitcnt lgkmcnt(1)
	v_mfma_f32_16x16x32_bf16 v[64:67], v[164:167], v[152:155], v[64:67]
	v_cvt_pk_bf16_f32 v163, v141, v143
	v_mfma_f32_16x16x32_bf16 v[52:55], v[164:167], v[156:159], v[52:55]
	v_cvt_pk_bf16_f32 v164, v124, v132
	v_cvt_pk_bf16_f32 v165, v130, v134
	v_cvt_pk_bf16_f32 v166, v136, v138
	s_waitcnt lgkmcnt(0)
	v_mfma_f32_16x16x32_bf16 v[152:155], v[184:187], v[152:155], v[60:63]
	s_nop 2
	ds_read_b64_tr_b16 v[60:61], v183 offset:18432
	ds_read_b64_tr_b16 v[62:63], v183 offset:20992
	v_cvt_pk_bf16_f32 v167, v140, v142
	v_mfma_f32_16x16x32_bf16 v[156:159], v[184:187], v[156:159], v[48:51]
	s_nop 2
	ds_read_b64_tr_b16 v[48:49], v183 offset:18464
	ds_read_b64_tr_b16 v[184:185], v183 offset:18496
	ds_read_b64_tr_b16 v[188:189], v183 offset:18528
	ds_read_b64_tr_b16 v[50:51], v183 offset:21024
	ds_read_b64_tr_b16 v[186:187], v183 offset:21056
	ds_read_b64_tr_b16 v[190:191], v183 offset:21088
	s_waitcnt lgkmcnt(6)
	v_mfma_f32_16x16x32_bf16 v[76:79], v[60:63], v[160:163], v[76:79]
	v_mfma_f32_16x16x32_bf16 v[72:75], v[60:63], v[164:167], v[68:71]
	s_waitcnt lgkmcnt(2)
	v_mfma_f32_16x16x32_bf16 v[60:63], v[48:51], v[160:163], v[148:151]
	v_mfma_f32_16x16x32_bf16 v[56:59], v[48:51], v[164:167], v[56:59]
	s_waitcnt lgkmcnt(1)
	v_mfma_f32_16x16x32_bf16 v[64:67], v[184:187], v[160:163], v[64:67]
	v_mfma_f32_16x16x32_bf16 v[48:51], v[184:187], v[164:167], v[52:55]
	s_waitcnt lgkmcnt(0)
	v_mfma_f32_16x16x32_bf16 v[68:71], v[188:191], v[160:163], v[152:155]
	v_mfma_f32_16x16x32_bf16 v[52:55], v[188:191], v[164:167], v[156:159]
	s_cbranch_scc1 .LBB0_736
	s_waitcnt vmcnt(2)
	ds_write_b128 v178, v[20:23] offset:23552
	s_waitcnt vmcnt(1)
	ds_write_b128 v180, v[24:27] offset:36864
	s_and_saveexec_b64 s[28:29], s[4:5]
	s_cbranch_execz .LBB0_735
	s_waitcnt vmcnt(0)
	ds_write_b128 v181, v[32:35] offset:23680

.LBB0_738:
	s_waitcnt lgkmcnt(0)
	s_barrier
	ds_read_b128 v[148:151], v182 offset:23552
	ds_read_b128 v[162:165], v182 offset:33664
	ds_read_b128 v[156:159], v182 offset:26880
	ds_read_b128 v[192:195], v182 offset:26944
	s_waitcnt lgkmcnt(3)
	v_mfma_f32_16x16x32_bf16 v[152:155], v[148:151], v[0:3], 0
	ds_read_b128 v[196:199], v182 offset:30208
	ds_read_b128 v[200:203], v182 offset:27008
	ds_read_b128 v[208:211], v182 offset:33536
	ds_read_b128 v[212:215], v182 offset:33600
	ds_read_b128 v[220:223], v182 offset:23616
	ds_read_b128 v[224:227], v182 offset:23680
	s_waitcnt lgkmcnt(7)
	v_mfma_f32_16x16x32_bf16 v[186:189], v[156:159], v[0:3], 0
	ds_read_b128 v[228:231], v182 offset:30272
	ds_read_b128 v[232:235], v182 offset:30336
	s_add_i32 s39, s31, -2
	s_cmp_ge_u32 s39, s30
	s_waitcnt lgkmcnt(3)
	v_mfma_f32_16x16x32_bf16 v[152:155], v[220:223], v[4:7], v[152:155]
	v_mfma_f32_16x16x32_bf16 v[204:207], v[196:199], v[0:3], 0
	v_mfma_f32_16x16x32_bf16 v[216:219], v[208:211], v[0:3], 0
	v_mfma_f32_16x16x32_bf16 v[186:189], v[192:195], v[4:7], v[186:189]
	s_waitcnt lgkmcnt(2)
	v_mfma_f32_16x16x32_bf16 v[152:155], v[224:227], v[16:19], v[152:155]
	s_waitcnt lgkmcnt(1)
	v_mfma_f32_16x16x32_bf16 v[204:207], v[228:231], v[4:7], v[204:207]
	v_mfma_f32_16x16x32_bf16 v[216:219], v[212:215], v[4:7], v[216:219]
	s_nop 4
	v_max3_f32 v97, v152, v153, v154
	v_mfma_f32_16x16x32_bf16 v[236:239], v[200:203], v[16:19], v[186:189]
	v_max_f32_e32 v97, v97, v155
	s_waitcnt lgkmcnt(0)
	v_mfma_f32_16x16x32_bf16 v[204:207], v[232:235], v[16:19], v[204:207]
	v_mfma_f32_16x16x32_bf16 v[216:219], v[162:165], v[16:19], v[216:219]
	s_nop 3
	v_max3_f32 v97, v97, v236, v237
	v_max3_f32 v97, v97, v238, v239
	s_nop 0
	v_max3_f32 v97, v97, v204, v205
	v_max3_f32 v97, v97, v206, v207
	v_mfma_f32_16x16x32_bf16 v[148:151], v[148:151], v[8:11], 0
	v_max3_f32 v97, v97, v216, v217
	v_max3_f32 v97, v97, v218, v219
	v_mov_b32_e32 v147, v97
	s_nop 1
	v_permlane16_swap_b32 v97, v147
	v_mfma_f32_16x16x32_bf16 v[156:159], v[156:159], v[8:11], 0
	s_waitcnt lgkmcnt(0)
	v_max_f32_e32 v97, v97, v147
	v_mov_b32_e32 v147, v97
	s_nop 1
	v_permlane32_swap_b32 v97, v147
	v_mfma_f32_16x16x32_bf16 v[208:211], v[208:211], v[8:11], 0
	s_waitcnt lgkmcnt(0)
	v_max_f32_e32 v97, v97, v147
	v_mul_f32_e32 v97, 0x3e16c740, v97
	v_max_f32_e32 v184, v146, v97
	v_sub_f32_e32 v97, v146, v184
	v_fma_f32 v146, v152, s37, -v184
	v_exp_f32_e32 v186, v146
	v_fma_f32 v146, v153, s37, -v184
	v_exp_f32_e32 v187, v146
	v_fma_f32 v146, v154, s37, -v184
	v_exp_f32_e32 v188, v146
	v_fma_f32 v146, v155, s37, -v184
	v_exp_f32_e32 v189, v146
	v_fma_f32 v146, v236, s37, -v184
	v_exp_f32_e32 v190, v146
	v_fma_f32 v146, v237, s37, -v184
	v_exp_f32_e32 v191, v146
	v_fma_f32 v146, v238, s37, -v184
	v_exp_f32_e32 v147, v146
	v_fma_f32 v146, v239, s37, -v184
	v_mfma_f32_16x16x32_bf16 v[220:223], v[220:223], v[12:15], v[148:151]
	v_exp_f32_e32 v168, v97
	s_nop 0
	v_pk_mul_f32 v[78:79], v[78:79], v[168:169] op_sel_hi:[1,0]
	v_mfma_f32_16x16x32_bf16 v[196:199], v[196:199], v[8:11], 0
	v_exp_f32_e32 v151, v146
	v_fma_f32 v146, v204, s37, -v184
	v_exp_f32_e32 v149, v146
	v_fma_f32 v146, v205, s37, -v184
	v_mfma_f32_16x16x32_bf16 v[192:195], v[192:195], v[12:15], v[156:159]
	v_exp_f32_e32 v155, v146
	v_fma_f32 v146, v206, s37, -v184
	v_exp_f32_e32 v153, v146
	v_fma_f32 v146, v207, s37, -v184
	v_mfma_f32_16x16x32_bf16 v[204:207], v[212:215], v[12:15], v[208:211]
	v_exp_f32_e32 v159, v146
	v_fma_f32 v146, v216, s37, -v184
	v_exp_f32_e32 v157, v146
	v_mfma_f32_16x16x32_bf16 v[208:211], v[224:227], v[44:47], v[220:223]
	v_fma_f32 v146, v217, s37, -v184
	v_exp_f32_e32 v161, v146
	v_fma_f32 v150, v218, s37, -v184
	v_mfma_f32_16x16x32_bf16 v[196:199], v[228:231], v[12:15], v[196:199]
	v_cvt_pk_bf16_f32 v216, v186, v187
	s_nop 2
	v_max3_f32 v146, v208, v209, v210
	v_mfma_f32_16x16x32_bf16 v[200:203], v[200:203], v[44:47], v[192:195]
	v_max_f32_e32 v146, v146, v211
	v_cvt_pk_bf16_f32 v217, v188, v189
	v_mfma_f32_16x16x32_bf16 v[212:215], v[232:235], v[44:47], v[196:199]
	v_cvt_pk_bf16_f32 v218, v190, v191
	s_nop 2
	v_max3_f32 v146, v146, v200, v201
	v_max3_f32 v146, v146, v202, v203
	v_mfma_f32_16x16x32_bf16 v[204:207], v[162:165], v[44:47], v[204:207]
	v_exp_f32_e32 v163, v150
	v_max3_f32 v146, v146, v212, v213
	v_max3_f32 v146, v146, v214, v215
	v_fma_f32 v150, v219, s37, -v184
	v_exp_f32_e32 v165, v150
	s_nop 2
	v_max3_f32 v146, v146, v204, v205
	v_max3_f32 v146, v146, v206, v207
	v_mov_b32_e32 v148, v146
	s_nop 1
	v_permlane16_swap_b32 v146, v148
	v_pk_mul_f32 v[76:77], v[76:77], v[168:169] op_sel_hi:[1,0]
	v_pk_mul_f32 v[62:63], v[62:63], v[168:169] op_sel_hi:[1,0]
	v_cvt_pk_bf16_f32 v219, v147, v151
	v_pk_mul_f32 v[60:61], v[60:61], v[168:169] op_sel_hi:[1,0]
	s_waitcnt lgkmcnt(0)
	v_max_f32_e32 v146, v146, v148
	v_mov_b32_e32 v148, v146
	s_nop 1
	v_permlane32_swap_b32 v146, v148
	v_pk_mul_f32 v[66:67], v[66:67], v[168:169] op_sel_hi:[1,0]
	v_pk_mul_f32 v[64:65], v[64:65], v[168:169] op_sel_hi:[1,0]
	v_pk_mul_f32 v[70:71], v[70:71], v[168:169] op_sel_hi:[1,0]
	v_pk_mul_f32 v[68:69], v[68:69], v[168:169] op_sel_hi:[1,0]
	s_waitcnt lgkmcnt(0)
	v_max_f32_e32 v97, v146, v148
	v_mul_f32_e32 v97, 0x3e16c740, v97
	v_max_f32_e32 v97, v145, v97
	v_fma_f32 v146, v208, s37, -v97
	v_exp_f32_e32 v192, v146
	v_fma_f32 v146, v209, s37, -v97
	v_exp_f32_e32 v193, v146
	v_fma_f32 v146, v210, s37, -v97
	v_exp_f32_e32 v194, v146
	v_fma_f32 v146, v211, s37, -v97
	v_exp_f32_e32 v195, v146
	v_fma_f32 v146, v200, s37, -v97
	v_exp_f32_e32 v196, v146
	v_fma_f32 v146, v201, s37, -v97
	v_sub_f32_e32 v145, v145, v97
	v_exp_f32_e32 v197, v146
	v_fma_f32 v146, v202, s37, -v97
	v_fma_f32 v148, v203, s37, -v97
	v_exp_f32_e32 v146, v146
	v_exp_f32_e32 v150, v148
	v_fma_f32 v148, v212, s37, -v97
	v_fma_f32 v152, v213, s37, -v97
	v_fma_f32 v162, v206, s37, -v97
	v_fma_f32 v164, v207, s37, -v97
	v_exp_f32_e32 v166, v145
	ds_read_b64_tr_b16 v[200:201], v183 offset:39424
	ds_read_b64_tr_b16 v[198:199], v183 offset:36864
	ds_read_b64_tr_b16 v[206:207], v183 offset:36896
	ds_read_b64_tr_b16 v[210:211], v183 offset:36928
	ds_read_b64_tr_b16 v[220:221], v183 offset:36960
	ds_read_b64_tr_b16 v[208:209], v183 offset:39456
	ds_read_b64_tr_b16 v[212:213], v183 offset:39488
	ds_read_b64_tr_b16 v[222:223], v183 offset:39520
	v_fma_f32 v156, v215, s37, -v97
	v_exp_f32_e32 v154, v152
	v_fma_f32 v152, v214, s37, -v97
	v_exp_f32_e32 v158, v156
	v_fma_f32 v156, v204, s37, -v97
	v_fma_f32 v160, v205, s37, -v97
	v_pk_mul_f32 v[74:75], v[74:75], v[166:167] op_sel_hi:[1,0]
	v_pk_mul_f32 v[72:73], v[72:73], v[166:167] op_sel_hi:[1,0]
	v_cvt_pk_bf16_f32 v202, v192, v193
	v_cvt_pk_bf16_f32 v203, v194, v195
	v_cvt_pk_bf16_f32 v204, v196, v197
	v_cvt_pk_bf16_f32 v205, v146, v150
	v_pk_mul_f32 v[58:59], v[58:59], v[166:167] op_sel_hi:[1,0]
	v_pk_mul_f32 v[56:57], v[56:57], v[166:167] op_sel_hi:[1,0]
	v_pk_mul_f32 v[50:51], v[50:51], v[166:167] op_sel_hi:[1,0]
	v_pk_mul_f32 v[48:49], v[48:49], v[166:167] op_sel_hi:[1,0]
	v_pk_mul_f32 v[54:55], v[54:55], v[166:167] op_sel_hi:[1,0]
	v_pk_mul_f32 v[52:53], v[52:53], v[166:167] op_sel_hi:[1,0]
	v_exp_f32_e32 v148, v148
	v_exp_f32_e32 v152, v152
	v_exp_f32_e32 v156, v156
	v_exp_f32_e32 v160, v160
	v_exp_f32_e32 v162, v162
	v_exp_f32_e32 v164, v164
	s_waitcnt lgkmcnt(6)
	v_mfma_f32_16x16x32_bf16 v[76:79], v[198:201], v[216:219], v[76:79]
	v_mfma_f32_16x16x32_bf16 v[72:75], v[198:201], v[202:205], v[72:75]
	v_cvt_pk_bf16_f32 v198, v149, v155
	v_cvt_pk_bf16_f32 v199, v153, v159
	v_cvt_pk_bf16_f32 v200, v157, v161
	s_waitcnt lgkmcnt(2)
	v_mfma_f32_16x16x32_bf16 v[60:63], v[206:209], v[216:219], v[60:63]
	v_cvt_pk_bf16_f32 v201, v163, v165
	v_mfma_f32_16x16x32_bf16 v[56:59], v[206:209], v[202:205], v[56:59]
	s_waitcnt lgkmcnt(1)
	v_mfma_f32_16x16x32_bf16 v[64:67], v[210:213], v[216:219], v[64:67]
	v_mfma_f32_16x16x32_bf16 v[48:51], v[210:213], v[202:205], v[48:51]
	v_cvt_pk_bf16_f32 v210, v148, v154
	v_cvt_pk_bf16_f32 v211, v152, v158
	v_cvt_pk_bf16_f32 v212, v156, v160
	s_waitcnt lgkmcnt(0)
	v_mfma_f32_16x16x32_bf16 v[206:209], v[220:223], v[216:219], v[68:71]
	s_nop 2
	ds_read_b64_tr_b16 v[68:69], v183 offset:41984
	ds_read_b64_tr_b16 v[70:71], v183 offset:44544
	v_cvt_pk_bf16_f32 v213, v162, v164
	v_mfma_f32_16x16x32_bf16 v[202:205], v[220:223], v[202:205], v[52:55]
	s_nop 2
	ds_read_b64_tr_b16 v[52:53], v183 offset:42016
	ds_read_b64_tr_b16 v[214:215], v183 offset:42048
	ds_read_b64_tr_b16 v[218:219], v183 offset:42080
	ds_read_b64_tr_b16 v[54:55], v183 offset:44576
	ds_read_b64_tr_b16 v[216:217], v183 offset:44608
	ds_read_b64_tr_b16 v[220:221], v183 offset:44640
	s_waitcnt lgkmcnt(6)
	v_mfma_f32_16x16x32_bf16 v[76:79], v[68:71], v[198:201], v[76:79]
	v_mfma_f32_16x16x32_bf16 v[68:71], v[68:71], v[210:213], v[72:75]
	s_waitcnt lgkmcnt(2)
	v_mfma_f32_16x16x32_bf16 v[72:75], v[52:55], v[198:201], v[60:63]
	v_mfma_f32_16x16x32_bf16 v[56:59], v[52:55], v[210:213], v[56:59]
	s_waitcnt lgkmcnt(1)
	v_mfma_f32_16x16x32_bf16 v[64:67], v[214:217], v[198:201], v[64:67]
	v_mfma_f32_16x16x32_bf16 v[52:55], v[214:217], v[210:213], v[48:51]
	s_waitcnt lgkmcnt(0)
	v_mfma_f32_16x16x32_bf16 v[60:63], v[218:221], v[198:201], v[206:209]
	v_mfma_f32_16x16x32_bf16 v[48:51], v[218:221], v[210:213], v[202:205]
	s_cbranch_scc1 .LBB0_742
	s_waitcnt vmcnt(2)
	ds_write_b128 v178, v[28:31]
	s_waitcnt vmcnt(1)
	ds_write_b128 v179, v[36:39] offset:13312
	s_and_saveexec_b64 s[28:29], s[4:5]
	s_cbranch_execz .LBB0_741
	s_waitcnt vmcnt(0)
	ds_write_b128 v181, v[40:43] offset:128
